# v64 + sentinel-poll address arithmetic moved from after the K-step barrier into the MFMA shadow (lever 8: VALU fill between MFMAs)
# speedup vs baseline: 1.0055x; 1.0055x over previous
.Lgin_tile:
	s_mul_hi_u32 s28, s0, s11
	s_mul_i32 vcc_lo, s28, s10
	s_sub_u32 vcc_lo, s0, vcc_lo
	s_lshr_b32 vcc_hi, vcc_lo, 3
	s_and_b32 vcc_lo, vcc_lo, 7
	s_lshl_b32 s28, s28, 3
	s_add_u32 s28, s28, vcc_lo
	s_lshl_b32 s20, s28, 19
	s_add_u32 s20, s20, 29876224
	s_add_u32 s20, s94, s20
	s_addc_u32 s21, s95, 0
	s_lshl_b32 s24, vcc_hi, 18
	s_add_u32 s24, s94, s24
	s_addc_u32 s25, s95, 0
	s_mul_i32 s26, s28, s12
	s_lshl_b32 s26, s26, 8
	s_lshl_b32 vcc_hi, vcc_hi, 8
	s_add_u32 s26, s26, vcc_hi
	s_add_u32 s26, s34, s26
	s_addc_u32 s27, s35, 0
	ds_write2_b32 v145, v145, v145 offset1:16
	s_mov_b32 exec_hi, 0
	ds_write_b32 v145, v145 offset:32768
	ds_write_b32 v145, v145 offset:32832
	s_mov_b32 exec_hi, -1
	s_waitcnt lgkmcnt(0)
	s_mov_b32 m0, s22
	s_nop 0
	global_load_lds_dwordx4 v251, s[20:21]
	s_add_u32 m0, m0, 0x1000
	s_add_u32 s20, s20, 0x10000
	s_addc_u32 s21, s21, 0
	global_load_lds_dwordx4 v251, s[20:21]
	s_add_u32 m0, m0, 0x1000
	s_add_u32 s20, s20, 0x10000
	s_addc_u32 s21, s21, 0
	global_load_lds_dwordx4 v251, s[20:21]
	s_add_u32 m0, m0, 0x1000
	s_add_u32 s20, s20, 0x10000
	s_addc_u32 s21, s21, 0
	global_load_lds_dwordx4 v251, s[20:21]
	s_add_u32 m0, m0, 0x1000
	s_add_u32 s20, s20, 0x10000
	s_addc_u32 s21, s21, 0
	global_load_lds_dwordx4 v251, s[20:21]
	s_add_u32 m0, m0, 0x1000
	s_add_u32 s20, s20, 0x10000
	s_addc_u32 s21, s21, 0
	global_load_lds_dwordx4 v251, s[20:21]
	s_add_u32 m0, m0, 0x1000
	s_add_u32 s20, s20, 0x10000
	s_addc_u32 s21, s21, 0
	global_load_lds_dwordx4 v251, s[20:21]
	s_add_u32 m0, m0, 0x1000
	s_add_u32 s20, s20, 0x10000
	s_addc_u32 s21, s21, 0
	global_load_lds_dwordx4 v251, s[20:21]
	s_add_u32 m0, m0, 0x1000
	s_sub_u32 s20, s20, 458624
	s_subb_u32 s21, s21, 0
	global_load_lds_dwordx4 v251, s[24:25]
	s_add_u32 m0, m0, 0x1000
	s_add_u32 s24, s24, 0x10000
	s_addc_u32 s25, s25, 0
	global_load_lds_dwordx4 v251, s[24:25]
	s_add_u32 m0, m0, 0x1000
	s_add_u32 s24, s24, 0x10000
	s_addc_u32 s25, s25, 0
	global_load_lds_dwordx4 v251, s[24:25]
	s_add_u32 m0, m0, 0x1000
	s_add_u32 s24, s24, 0x10000
	s_addc_u32 s25, s25, 0
	global_load_lds_dwordx4 v251, s[24:25]
	s_sub_u32 s24, s24, 196480
	s_subb_u32 s25, s25, 0
	v_mov_b32_e32 v0, 0
	v_mov_b32_e32 v1, 0
	v_mov_b32_e32 v2, 0
	v_mov_b32_e32 v3, 0
	v_mov_b32_e32 v4, 0
	v_mov_b32_e32 v5, 0
	v_mov_b32_e32 v6, 0
	v_mov_b32_e32 v7, 0
	v_mov_b32_e32 v8, 0
	v_mov_b32_e32 v9, 0
	v_mov_b32_e32 v10, 0
	v_mov_b32_e32 v11, 0
	v_mov_b32_e32 v12, 0
	v_mov_b32_e32 v13, 0
	v_mov_b32_e32 v14, 0
	v_mov_b32_e32 v15, 0
	v_mov_b32_e32 v16, 0
	v_mov_b32_e32 v17, 0
	v_mov_b32_e32 v18, 0
	v_mov_b32_e32 v19, 0
	v_mov_b32_e32 v20, 0
	v_mov_b32_e32 v21, 0
	v_mov_b32_e32 v22, 0
	v_mov_b32_e32 v23, 0
	v_mov_b32_e32 v24, 0
	v_mov_b32_e32 v25, 0
	v_mov_b32_e32 v26, 0
	v_mov_b32_e32 v27, 0
	v_mov_b32_e32 v28, 0
	v_mov_b32_e32 v29, 0
	v_mov_b32_e32 v30, 0
	v_mov_b32_e32 v31, 0
	v_mov_b32_e32 v32, 0
	v_mov_b32_e32 v33, 0
	v_mov_b32_e32 v34, 0
	v_mov_b32_e32 v35, 0
	v_mov_b32_e32 v36, 0
	v_mov_b32_e32 v37, 0
	v_mov_b32_e32 v38, 0
	v_mov_b32_e32 v39, 0
	v_mov_b32_e32 v40, 0
	v_mov_b32_e32 v41, 0
	v_mov_b32_e32 v42, 0
	v_mov_b32_e32 v43, 0
	v_mov_b32_e32 v44, 0
	v_mov_b32_e32 v45, 0
	v_mov_b32_e32 v46, 0
	v_mov_b32_e32 v47, 0
	v_mov_b32_e32 v48, 0
	v_mov_b32_e32 v49, 0
	v_mov_b32_e32 v50, 0
	v_mov_b32_e32 v51, 0
	v_mov_b32_e32 v52, 0
	v_mov_b32_e32 v53, 0
	v_mov_b32_e32 v54, 0
	v_mov_b32_e32 v55, 0
	v_mov_b32_e32 v56, 0
	v_mov_b32_e32 v57, 0
	v_mov_b32_e32 v58, 0
	v_mov_b32_e32 v59, 0
	v_mov_b32_e32 v60, 0
	v_mov_b32_e32 v61, 0
	v_mov_b32_e32 v62, 0
	v_mov_b32_e32 v63, 0
	v_mov_b32_e32 v64, 0
	v_mov_b32_e32 v65, 0
	v_mov_b32_e32 v66, 0
	v_mov_b32_e32 v67, 0
	v_mov_b32_e32 v68, 0
	v_mov_b32_e32 v69, 0
	v_mov_b32_e32 v70, 0
	v_mov_b32_e32 v71, 0
	v_mov_b32_e32 v72, 0
	v_mov_b32_e32 v73, 0
	v_mov_b32_e32 v74, 0
	v_mov_b32_e32 v75, 0
	v_mov_b32_e32 v76, 0
	v_mov_b32_e32 v77, 0
	v_mov_b32_e32 v78, 0
	v_mov_b32_e32 v79, 0
	v_mov_b32_e32 v80, 0
	v_mov_b32_e32 v81, 0
	v_mov_b32_e32 v82, 0
	v_mov_b32_e32 v83, 0
	v_mov_b32_e32 v84, 0
	v_mov_b32_e32 v85, 0
	v_mov_b32_e32 v86, 0
	v_mov_b32_e32 v87, 0
	v_mov_b32_e32 v88, 0
	v_mov_b32_e32 v89, 0
	v_mov_b32_e32 v90, 0
	v_mov_b32_e32 v91, 0
	v_mov_b32_e32 v92, 0
	v_mov_b32_e32 v93, 0
	v_mov_b32_e32 v94, 0
	v_mov_b32_e32 v95, 0
	v_mov_b32_e32 v96, 0
	v_mov_b32_e32 v97, 0
	v_mov_b32_e32 v98, 0
	v_mov_b32_e32 v99, 0
	v_mov_b32_e32 v100, 0
	v_mov_b32_e32 v101, 0
	v_mov_b32_e32 v102, 0
	v_mov_b32_e32 v103, 0
	v_mov_b32_e32 v104, 0
	v_mov_b32_e32 v105, 0
	v_mov_b32_e32 v106, 0
	v_mov_b32_e32 v107, 0
	v_mov_b32_e32 v108, 0
	v_mov_b32_e32 v109, 0
	v_mov_b32_e32 v110, 0
	v_mov_b32_e32 v111, 0
	v_mov_b32_e32 v112, 0
	v_mov_b32_e32 v113, 0
	v_mov_b32_e32 v114, 0
	v_mov_b32_e32 v115, 0
	v_mov_b32_e32 v116, 0
	v_mov_b32_e32 v117, 0
	v_mov_b32_e32 v118, 0
	v_mov_b32_e32 v119, 0
	v_mov_b32_e32 v120, 0
	v_mov_b32_e32 v121, 0
	v_mov_b32_e32 v122, 0
	v_mov_b32_e32 v123, 0
	v_mov_b32_e32 v124, 0
	v_mov_b32_e32 v125, 0
	v_mov_b32_e32 v126, 0
	v_mov_b32_e32 v127, 0
	v_and_b32_e32 v128, 63, v193
	v_and_b32_e32 v129, 15, v193
	v_lshlrev_b32_e32 v128, 7, v128
	v_lshl_add_u32 v128, v129, 2, v128
	v_add_u32_e32 v129, 8192, v128
	v_add_u32_e32 v130, 16384, v128
	v_add_u32_e32 v131, 24576, v128
	v_add_u32_e32 v132, 32768, v128
	v_add_u32_e32 v133, 40960, v128
	s_mov_b32 s16, 16
.Lgin_k:
	s_setprio 2
	s_waitcnt vmcnt(0)
	s_barrier
	s_mov_b32 s28, 64

.Lgin_nodma:
	s_setprio 0
	v_mfma_f32_32x32x16_bf16 v[0:15], v[216:219], v[128:131], v[0:15]
	v_mfma_f32_32x32x16_bf16 v[16:31], v[232:235], v[128:131], v[16:31]
	v_mfma_f32_32x32x16_bf16 v[32:47], v[216:219], v[148:151], v[32:47]
	v_mfma_f32_32x32x16_bf16 v[48:63], v[232:235], v[148:151], v[48:63]
	v_mfma_f32_32x32x16_bf16 v[64:79], v[216:219], v[164:167], v[64:79]
	v_mfma_f32_32x32x16_bf16 v[80:95], v[232:235], v[164:167], v[80:95]
	v_mfma_f32_32x32x16_bf16 v[96:111], v[216:219], v[180:183], v[96:111]
	v_mfma_f32_32x32x16_bf16 v[112:127], v[232:235], v[180:183], v[112:127]
	v_mfma_f32_32x32x16_bf16 v[0:15], v[220:223], v[132:135], v[0:15]
	v_mfma_f32_32x32x16_bf16 v[16:31], v[236:239], v[132:135], v[16:31]
	v_mfma_f32_32x32x16_bf16 v[32:47], v[220:223], v[152:155], v[32:47]
	v_mfma_f32_32x32x16_bf16 v[48:63], v[236:239], v[152:155], v[48:63]
	v_mfma_f32_32x32x16_bf16 v[64:79], v[220:223], v[168:171], v[64:79]
	v_mfma_f32_32x32x16_bf16 v[80:95], v[236:239], v[168:171], v[80:95]
	v_mfma_f32_32x32x16_bf16 v[96:111], v[220:223], v[184:187], v[96:111]
	v_mfma_f32_32x32x16_bf16 v[112:127], v[236:239], v[184:187], v[112:127]
	v_mfma_f32_32x32x16_bf16 v[0:15], v[224:227], v[136:139], v[0:15]
	v_mfma_f32_32x32x16_bf16 v[16:31], v[240:243], v[136:139], v[16:31]
	v_mfma_f32_32x32x16_bf16 v[32:47], v[224:227], v[156:159], v[32:47]
	v_mfma_f32_32x32x16_bf16 v[48:63], v[240:243], v[156:159], v[48:63]
	v_and_b32_e32 v128, 63, v193
	v_and_b32_e32 v129, 15, v193
	v_lshlrev_b32_e32 v128, 7, v128
	v_lshl_add_u32 v128, v129, 2, v128
	v_add_u32_e32 v129, 8192, v128
	v_add_u32_e32 v130, 16384, v128
	v_add_u32_e32 v131, 24576, v128
	v_add_u32_e32 v132, 32768, v128
	v_add_u32_e32 v133, 40960, v128
	v_mfma_f32_32x32x16_bf16 v[64:79], v[224:227], v[172:175], v[64:79]
	v_mfma_f32_32x32x16_bf16 v[80:95], v[240:243], v[172:175], v[80:95]
	v_mfma_f32_32x32x16_bf16 v[96:111], v[224:227], v[188:191], v[96:111]
	v_mfma_f32_32x32x16_bf16 v[112:127], v[240:243], v[188:191], v[112:127]
	v_mfma_f32_32x32x16_bf16 v[0:15], v[228:231], v[140:143], v[0:15]
	v_mfma_f32_32x32x16_bf16 v[16:31], v[244:247], v[140:143], v[16:31]
	v_mfma_f32_32x32x16_bf16 v[32:47], v[228:231], v[160:163], v[32:47]
	v_mfma_f32_32x32x16_bf16 v[48:63], v[244:247], v[160:163], v[48:63]
	v_mfma_f32_32x32x16_bf16 v[64:79], v[228:231], v[176:179], v[64:79]
	v_mfma_f32_32x32x16_bf16 v[80:95], v[244:247], v[176:179], v[80:95]
	v_mfma_f32_32x32x16_bf16 v[96:111], v[228:231], v[212:215], v[96:111]
	v_mfma_f32_32x32x16_bf16 v[112:127], v[244:247], v[212:215], v[112:127]
	s_sub_u32 s16, s16, 1
	s_cmp_lg_u32 s16, 0
	s_cbranch_scc1 .Lgin_k
	s_nop 15
	s_nop 3
	v_and_b32_e32 v215, 31, v193
	v_mul_u32_u24_e32 v212, 0x110, v215
	v_bfe_u32 v215, v193, 5, 1
	v_lshl_add_u32 v212, v215, 3, v212
	v_bfe_u32 v215, v193, 7, 1
	v_mov_b32_e32 v216, 34816
	v_mad_u32_u24 v212, v215, v216, v212
	v_bfe_u32 v215, v193, 6, 1
	v_lshl_add_u32 v212, v215, 7, v212
	v_cvt_pk_bf16_f32 v128, v0, v1
	v_cvt_pk_bf16_f32 v129, v2, v3
	ds_write_b64 v212, v[128:129] offset:0
	v_cvt_pk_bf16_f32 v130, v4, v5
	v_cvt_pk_bf16_f32 v131, v6, v7
	ds_write_b64 v212, v[130:131] offset:16
	v_cvt_pk_bf16_f32 v132, v8, v9
	v_cvt_pk_bf16_f32 v133, v10, v11
	ds_write_b64 v212, v[132:133] offset:32
	v_cvt_pk_bf16_f32 v134, v12, v13
	v_cvt_pk_bf16_f32 v135, v14, v15
	ds_write_b64 v212, v[134:135] offset:48
	v_cvt_pk_bf16_f32 v136, v16, v17
	v_cvt_pk_bf16_f32 v137, v18, v19
	ds_write_b64 v212, v[136:137] offset:64
	v_cvt_pk_bf16_f32 v138, v20, v21
	v_cvt_pk_bf16_f32 v139, v22, v23
	ds_write_b64 v212, v[138:139] offset:80
	v_cvt_pk_bf16_f32 v140, v24, v25
	v_cvt_pk_bf16_f32 v141, v26, v27
	ds_write_b64 v212, v[140:141] offset:96
	v_cvt_pk_bf16_f32 v142, v28, v29
	v_cvt_pk_bf16_f32 v143, v30, v31
	ds_write_b64 v212, v[142:143] offset:112
	v_cvt_pk_bf16_f32 v128, v32, v33
	v_cvt_pk_bf16_f32 v129, v34, v35
	ds_write_b64 v212, v[128:129] offset:8704
	v_cvt_pk_bf16_f32 v130, v36, v37
	v_cvt_pk_bf16_f32 v131, v38, v39
	ds_write_b64 v212, v[130:131] offset:8720
	v_cvt_pk_bf16_f32 v132, v40, v41
	v_cvt_pk_bf16_f32 v133, v42, v43
	ds_write_b64 v212, v[132:133] offset:8736
	v_cvt_pk_bf16_f32 v134, v44, v45
	v_cvt_pk_bf16_f32 v135, v46, v47
	ds_write_b64 v212, v[134:135] offset:8752
	v_cvt_pk_bf16_f32 v136, v48, v49
	v_cvt_pk_bf16_f32 v137, v50, v51
	ds_write_b64 v212, v[136:137] offset:8768
	v_cvt_pk_bf16_f32 v138, v52, v53
	v_cvt_pk_bf16_f32 v139, v54, v55
	ds_write_b64 v212, v[138:139] offset:8784
	v_cvt_pk_bf16_f32 v140, v56, v57
	v_cvt_pk_bf16_f32 v141, v58, v59
	ds_write_b64 v212, v[140:141] offset:8800
	v_cvt_pk_bf16_f32 v142, v60, v61
	v_cvt_pk_bf16_f32 v143, v62, v63
	ds_write_b64 v212, v[142:143] offset:8816
	v_cvt_pk_bf16_f32 v128, v64, v65
	v_cvt_pk_bf16_f32 v129, v66, v67
	ds_write_b64 v212, v[128:129] offset:17408
	v_cvt_pk_bf16_f32 v130, v68, v69
	v_cvt_pk_bf16_f32 v131, v70, v71
	ds_write_b64 v212, v[130:131] offset:17424
	v_cvt_pk_bf16_f32 v132, v72, v73
	v_cvt_pk_bf16_f32 v133, v74, v75
	ds_write_b64 v212, v[132:133] offset:17440
	v_cvt_pk_bf16_f32 v134, v76, v77
	v_cvt_pk_bf16_f32 v135, v78, v79
	ds_write_b64 v212, v[134:135] offset:17456
	v_cvt_pk_bf16_f32 v136, v80, v81
	v_cvt_pk_bf16_f32 v137, v82, v83
	ds_write_b64 v212, v[136:137] offset:17472
	v_cvt_pk_bf16_f32 v138, v84, v85
	v_cvt_pk_bf16_f32 v139, v86, v87
	ds_write_b64 v212, v[138:139] offset:17488
	v_cvt_pk_bf16_f32 v140, v88, v89
	v_cvt_pk_bf16_f32 v141, v90, v91
	ds_write_b64 v212, v[140:141] offset:17504
	v_cvt_pk_bf16_f32 v142, v92, v93
	v_cvt_pk_bf16_f32 v143, v94, v95
	ds_write_b64 v212, v[142:143] offset:17520
	v_cvt_pk_bf16_f32 v128, v96, v97
	v_cvt_pk_bf16_f32 v129, v98, v99
	ds_write_b64 v212, v[128:129] offset:26112
	v_cvt_pk_bf16_f32 v130, v100, v101
	v_cvt_pk_bf16_f32 v131, v102, v103
	ds_write_b64 v212, v[130:131] offset:26128
	v_cvt_pk_bf16_f32 v132, v104, v105
	v_cvt_pk_bf16_f32 v133, v106, v107
	ds_write_b64 v212, v[132:133] offset:26144
	v_cvt_pk_bf16_f32 v134, v108, v109
	v_cvt_pk_bf16_f32 v135, v110, v111
	ds_write_b64 v212, v[134:135] offset:26160
	v_cvt_pk_bf16_f32 v136, v112, v113
	v_cvt_pk_bf16_f32 v137, v114, v115
	ds_write_b64 v212, v[136:137] offset:26176
	v_cvt_pk_bf16_f32 v138, v116, v117
	v_cvt_pk_bf16_f32 v139, v118, v119
	ds_write_b64 v212, v[138:139] offset:26192
	v_cvt_pk_bf16_f32 v140, v120, v121
	v_cvt_pk_bf16_f32 v141, v122, v123
	ds_write_b64 v212, v[140:141] offset:26208
	v_cvt_pk_bf16_f32 v142, v124, v125
	v_cvt_pk_bf16_f32 v143, v126, v127
	ds_write_b64 v212, v[142:143] offset:26224
	s_waitcnt lgkmcnt(0)
	s_barrier
	v_lshrrev_b32_e32 v215, 4, v193
	v_and_b32_e32 v216, 15, v193
	v_mul_u32_u24_e32 v213, 0x110, v215
	v_lshl_add_u32 v213, v216, 4, v213
	v_mul_lo_u32 v214, v215, s12
	v_lshl_add_u32 v214, v216, 4, v214
	s_lshl_b32 s28, s12, 4
	ds_read_b128 v[148:151], v213 offset:0
	ds_read_b128 v[152:155], v213 offset:4352
	ds_read_b128 v[156:159], v213 offset:8704
	ds_read_b128 v[160:163], v213 offset:13056
	ds_read_b128 v[164:167], v213 offset:17408
	ds_read_b128 v[168:171], v213 offset:21760
	ds_read_b128 v[172:175], v213 offset:26112
	ds_read_b128 v[176:179], v213 offset:30464
	ds_read_b128 v[180:183], v213 offset:34816
	ds_read_b128 v[184:187], v213 offset:39168
	ds_read_b128 v[188:191], v213 offset:43520
	ds_read_b128 v[220:223], v213 offset:47872
	ds_read_b128 v[224:227], v213 offset:52224
	ds_read_b128 v[228:231], v213 offset:56576
	ds_read_b128 v[232:235], v213 offset:60928
	ds_read_b128 v[236:239], v213 offset:65280
	s_waitcnt lgkmcnt(15)
	global_store_dwordx4 v214, v[148:151], s[26:27]
	s_add_u32 s26, s26, s28
	s_addc_u32 s27, s27, 0
	s_waitcnt lgkmcnt(14)
	global_store_dwordx4 v214, v[152:155], s[26:27]
	s_add_u32 s26, s26, s28
	s_addc_u32 s27, s27, 0
	s_waitcnt lgkmcnt(13)
	global_store_dwordx4 v214, v[156:159], s[26:27]
	s_add_u32 s26, s26, s28
	s_addc_u32 s27, s27, 0
	s_waitcnt lgkmcnt(12)
	global_store_dwordx4 v214, v[160:163], s[26:27]
	s_add_u32 s26, s26, s28
	s_addc_u32 s27, s27, 0
	s_waitcnt lgkmcnt(11)
	global_store_dwordx4 v214, v[164:167], s[26:27]
	s_add_u32 s26, s26, s28
	s_addc_u32 s27, s27, 0
	s_waitcnt lgkmcnt(10)
	global_store_dwordx4 v214, v[168:171], s[26:27]
	s_add_u32 s26, s26, s28
	s_addc_u32 s27, s27, 0
	s_waitcnt lgkmcnt(9)
	global_store_dwordx4 v214, v[172:175], s[26:27]
	s_add_u32 s26, s26, s28
	s_addc_u32 s27, s27, 0
	s_waitcnt lgkmcnt(8)
	global_store_dwordx4 v214, v[176:179], s[26:27]
	s_add_u32 s26, s26, s28
	s_addc_u32 s27, s27, 0
	s_waitcnt lgkmcnt(7)
	global_store_dwordx4 v214, v[180:183], s[26:27]
	s_add_u32 s26, s26, s28
	s_addc_u32 s27, s27, 0
	s_waitcnt lgkmcnt(6)
	global_store_dwordx4 v214, v[184:187], s[26:27]
	s_add_u32 s26, s26, s28
	s_addc_u32 s27, s27, 0
	s_waitcnt lgkmcnt(5)
	global_store_dwordx4 v214, v[188:191], s[26:27]
	s_add_u32 s26, s26, s28
	s_addc_u32 s27, s27, 0
	s_waitcnt lgkmcnt(4)
	global_store_dwordx4 v214, v[220:223], s[26:27]
	s_add_u32 s26, s26, s28
	s_addc_u32 s27, s27, 0
	s_waitcnt lgkmcnt(3)
	global_store_dwordx4 v214, v[224:227], s[26:27]
	s_add_u32 s26, s26, s28
	s_addc_u32 s27, s27, 0
	s_waitcnt lgkmcnt(2)
	global_store_dwordx4 v214, v[228:231], s[26:27]
	s_add_u32 s26, s26, s28
	s_addc_u32 s27, s27, 0
	s_waitcnt lgkmcnt(1)
	global_store_dwordx4 v214, v[232:235], s[26:27]
	s_add_u32 s26, s26, s28
	s_addc_u32 s27, s27, 0
	s_waitcnt lgkmcnt(0)
	global_store_dwordx4 v214, v[236:239], s[26:27]
	s_barrier
	s_add_u32 s0, s0, s6
	s_cmp_lt_u32 s0, s1
	s_cbranch_scc1 .Lgin_tile
	v_mov_b32_e32 v145, 0
